# adds: low-rank gate weight rows of gla_prep loaded in one batch
# speedup vs baseline: 1.0027x; 1.0027x over previous
;   __device__ __forceinline__ bf16* h() const { unsigned o_ = (unsigned)(OFF_h); asm volatile("" : "+s"(o_)); return (bf16*)(ws + o_); }
;   __device__ __forceinline__ bf16* U() const { unsigned o_ = (unsigned)(OFF_U); asm volatile("" : "+s"(o_)); return (bf16*)(ws + o_); }
; #define UNPK8(v, f) { f[0] = lo16(v.x); f[1] = hi16(v.x); f[2] = lo16(v.y); f[3] = hi16(v.y); f[4] = lo16(v.z); f[5] = hi16(v.z); f[6] = lo16(v.w); f[7] = hi16(v.w); }
; __device__ void gla_prep_unit(const P& p, int layer, int unit, char* smem) {
;     ...
;   uint4 qv_pre, kv_pre;
;   {
;     const int t = tid >> 2, d0 = (tid & 3) * 8;
;     qv_pre = *(const uint4*)(p.U() + TROW(t) * US + C_GQ + h * 32 + d0);
;     kv_pre = *(const uint4*)(p.U() + TROW(t) * US + C_GK + h * 32 + d0);
;   }
;   __syncthreads();
;   {
;     const int t = tid >> 2, d0 = (tid & 3) * 8;
;     const bf16* cp = p.U() + TROW(t) * US + C_GC;
;     const uint4 c0 = *(const uint4*)cp, c1 = *(const uint4*)(cp + 8);
;     float cv[16];
;     { float f[8]; UNPK8(c0, f);
; #pragma unroll
;       for (int i = 0; i < 8; ++i) cv[i] = f[i];
;       UNPK8(c1, f);
; #pragma unroll
;       for (int i = 0; i < 8; ++i) cv[8 + i] = f[i]; }
;     const float* wg = p.gla_wg + (size_t)layer * 16 * 128 + h * 32 + d0;
;     float acc[8];
;     {
;       const float4 b0 = *(const float4*)(p.gla_bg + layer * 128 + h * 32 + d0), b1 = *(const float4*)(p.gla_bg + layer * 128 + h * 32 + d0 + 4);
;       acc[0] = b0.x; acc[1] = b0.y; acc[2] = b0.z; acc[3] = b0.w; acc[4] = b1.x; acc[5] = b1.y; acc[6] = b1.z; acc[7] = b1.w;
;     }
; #pragma unroll
;     for (int rr = 0; rr < 16; ++rr) {
;       const float4 w0 = *(const float4*)(wg + rr * 128), w1 = *(const float4*)(wg + rr * 128 + 4);
;       acc[0] += cv[rr] * w0.x; acc[1] += cv[rr] * w0.y; acc[2] += cv[rr] * w0.z; acc[3] += cv[rr] * w0.w;
;       acc[4] += cv[rr] * w1.x; acc[5] += cv[rr] * w1.y; acc[6] += cv[rr] * w1.z; acc[7] += cv[rr] * w1.w;
;     }
.LBB0_250:
	s_mul_i32 s0, s33, 0xfc1
	s_lshr_b32 s1, s0, 18
	s_mulk_i32 s1, 0x41
	s_sub_i32 s2, s33, s1
	s_bfe_u32 s22, s0, 0x20012
	s_lshr_b32 s0, s0, 20
	s_lshl_b32 s3, s2, 7
	s_mul_i32 s1, s0, 0x2010
	s_and_b32 s3, s3, 0xff80
	v_mov_b32_e32 v30, v136
	s_add_i32 s19, s3, s1
	s_mul_i32 s20, s0, 0x70
	s_mov_b32 s0, 0x6180000
	s_addk_i32 s19, 0xff90
	s_addk_i32 s20, 0x4020
	s_add_u32 s0, s76, s0
	s_addc_u32 s1, s77, 0
	s_and_b32 s2, s2, 0xffff
	v_ashrrev_i32_e32 v31, 2, v30
	s_cmp_eq_u32 s2, 0
	v_lshlrev_b32_e32 v0, 3, v30
	s_cselect_b64 s[14:15], -1, 0
	v_cmp_gt_i32_e32 vcc, s44, v31
	v_and_b32_e32 v32, 24, v0
	s_and_b64 vcc, s[14:15], vcc
	v_mov_b32_e32 v0, s19
	v_mov_b32_e32 v1, s20
	v_cndmask_b32_e32 v0, v0, v1, vcc
	v_add_u32_e32 v33, v0, v31
	v_mov_b64_e32 v[0:1], s[0:1]
	v_mad_i64_i32 v[0:1], s[0:1], v33, s54, v[0:1]
	s_lshl_b32 s96, s22, 6
	v_lshl_add_u64 v[0:1], v[0:1], 0, s[96:97]
	v_lshlrev_b32_e32 v138, 1, v32
	v_lshl_add_u64 v[0:1], v[0:1], 0, v[138:139]
	s_mov_b32 s0, 0x6180000
	global_load_dwordx4 v[0:3], v[0:1], off offset:1536
	s_add_u32 s0, s76, s0
	s_addc_u32 s1, s77, 0
	v_mov_b64_e32 v[4:5], s[0:1]
	v_mad_i64_i32 v[4:5], s[0:1], v33, s54, v[4:5]
	v_lshl_add_u64 v[4:5], v[4:5], 0, s[96:97]
	v_lshl_add_u64 v[4:5], v[4:5], 0, v[138:139]
	s_mov_b32 s0, 0x6180000
	global_load_dwordx4 v[4:7], v[4:5], off offset:1792
	s_barrier
	s_add_u32 s0, s76, s0
	s_addc_u32 s1, s77, 0
	v_mov_b64_e32 v[8:9], s[0:1]
	v_mad_i64_i32 v[12:13], s[0:1], v33, s54, v[8:9]
	global_load_dwordx4 v[8:11], v[12:13], off offset:3088
	s_nop 0
	global_load_dwordx4 v[12:15], v[12:13], off offset:3072
	s_lshl_b32 s21, s22, 7
	s_add_u32 s0, s62, s21
	s_addc_u32 s1, s63, 0
	s_add_u32 s2, s56, s21
	v_lshlrev_b32_e32 v26, 2, v32
	s_addc_u32 s3, s66, 0
	v_mov_b32_e32 v27, v139
	v_lshl_add_u64 v[18:19], s[0:1], 0, v[26:27]
	s_waitcnt vmcnt(1)
	v_lshlrev_b32_e32 v28, 16, v8
	s_waitcnt vmcnt(0)
	v_lshlrev_b32_e32 v42, 16, v12
	v_and_b32_e32 v43, 0xffff0000, v12
	v_lshlrev_b32_e32 v44, 16, v13
	v_and_b32_e32 v45, 0xffff0000, v13
	v_lshlrev_b32_e32 v46, 16, v14
	v_and_b32_e32 v47, 0xffff0000, v14
	v_lshlrev_b32_e32 v22, 16, v15
	v_and_b32_e32 v23, 0xffff0000, v15
	v_and_b32_e32 v29, 0xffff0000, v8
	v_lshlrev_b32_e32 v20, 16, v9
	v_and_b32_e32 v21, 0xffff0000, v9
	v_lshlrev_b32_e32 v16, 16, v10
	v_and_b32_e32 v17, 0xffff0000, v10
	v_lshlrev_b32_e32 v24, 16, v11
	v_and_b32_e32 v25, 0xffff0000, v11
	global_load_dwordx4 v[8:11], v26, s[2:3] offset:16
	global_load_dwordx4 v[12:15], v26, s[2:3]
	global_load_dwordx4 v[34:37], v26, s[0:1] offset:16
	global_load_dwordx4 v[38:41], v26, s[0:1]
	global_load_dwordx4 v[164:167], v26, s[0:1] offset:528
	global_load_dwordx4 v[168:171], v26, s[0:1] offset:512
	global_load_dwordx4 v[172:175], v26, s[0:1] offset:1040
	global_load_dwordx4 v[176:179], v26, s[0:1] offset:1024
	global_load_dwordx4 v[180:183], v26, s[0:1] offset:1552
	global_load_dwordx4 v[184:187], v26, s[0:1] offset:1536
	global_load_dwordx4 v[210:213], v26, s[0:1] offset:2064
	global_load_dwordx4 v[214:217], v26, s[0:1] offset:2048
	global_load_dwordx4 v[218:221], v26, s[0:1] offset:2576
	global_load_dwordx4 v[222:225], v26, s[0:1] offset:2560
	s_mov_b32 s2, 0x3d800000
	s_waitcnt vmcnt(11)
	v_fma_f32 v50, v34, v42, v8
	s_waitcnt vmcnt(0)
	v_fma_f32 v27, v38, v42, v12
	v_fma_f32 v12, v39, v42, v13
	v_fma_f32 v14, v40, v42, v14
	v_fmac_f32_e32 v15, v41, v42
	v_fma_f32 v51, v35, v42, v9
	v_fma_f32 v10, v36, v42, v10
	v_fmac_f32_e32 v11, v37, v42
	s_nop 0
	s_nop 0
	s_waitcnt vmcnt(1)
	v_fmac_f32_e32 v50, v164, v43
	s_waitcnt vmcnt(0)
	v_fmac_f32_e32 v27, v168, v43
	v_fmac_f32_e32 v12, v169, v43
	v_fmac_f32_e32 v14, v170, v43
	v_fmac_f32_e32 v15, v171, v43
	v_fmac_f32_e32 v51, v165, v43
	v_fmac_f32_e32 v10, v166, v43
	v_fmac_f32_e32 v11, v167, v43
	s_nop 0
	s_nop 0
	s_waitcnt vmcnt(1)
	v_fmac_f32_e32 v50, v172, v44
	s_waitcnt vmcnt(0)
	v_fmac_f32_e32 v27, v176, v44
	v_fmac_f32_e32 v12, v177, v44
	v_fmac_f32_e32 v14, v178, v44
	v_fmac_f32_e32 v15, v179, v44
	v_fmac_f32_e32 v51, v173, v44
	v_fmac_f32_e32 v10, v174, v44
	v_fmac_f32_e32 v11, v175, v44
	s_nop 0
	s_nop 0
	s_waitcnt vmcnt(1)
	v_fmac_f32_e32 v50, v180, v45
	s_waitcnt vmcnt(0)
	v_fmac_f32_e32 v27, v184, v45
	v_fmac_f32_e32 v12, v185, v45
	v_fmac_f32_e32 v14, v186, v45
	v_fmac_f32_e32 v15, v187, v45
	v_fmac_f32_e32 v51, v181, v45
	v_fmac_f32_e32 v10, v182, v45
	v_fmac_f32_e32 v11, v183, v45
	s_nop 0
	s_nop 0
	s_waitcnt vmcnt(1)
	v_fmac_f32_e32 v50, v210, v46
	s_waitcnt vmcnt(0)
	v_fmac_f32_e32 v27, v214, v46
	v_fmac_f32_e32 v12, v215, v46
	v_fmac_f32_e32 v14, v216, v46
	v_fmac_f32_e32 v15, v217, v46
	v_fmac_f32_e32 v51, v211, v46
	v_fmac_f32_e32 v10, v212, v46
	v_fmac_f32_e32 v11, v213, v46
	s_nop 0
	s_nop 0
	s_waitcnt vmcnt(1)
	v_fmac_f32_e32 v50, v218, v47
	s_waitcnt vmcnt(0)
	v_fmac_f32_e32 v27, v222, v47
	v_fmac_f32_e32 v12, v223, v47
	v_fmac_f32_e32 v14, v224, v47
	v_fmac_f32_e32 v15, v225, v47
	v_fmac_f32_e32 v51, v219, v47
	v_fmac_f32_e32 v10, v220, v47
	v_fmac_f32_e32 v11, v221, v47
	global_load_dwordx4 v[34:37], v26, s[0:1] offset:3088
	global_load_dwordx4 v[38:41], v26, s[0:1] offset:3072
	global_load_dwordx4 v[42:45], v26, s[0:1] offset:3600
	global_load_dwordx4 v[46:49], v26, s[0:1] offset:3584
	s_mov_b64 s[0:1], 0x1000
	s_waitcnt vmcnt(2)
	v_mov_b32_e32 v8, v39
	s_waitcnt vmcnt(0)
; __device__ void gla_prep_unit(const P& p, int layer, int unit, char* smem) {
;     ...
; #pragma unroll
;     for (int rr = 0; rr < 16; ++rr) {
;       const float4 w0 = *(const float4*)(wg + rr * 128), w1 = *(const float4*)(wg + rr * 128 + 4);
;       acc[0] += cv[rr] * w0.x; acc[1] += cv[rr] * w0.y; acc[2] += cv[rr] * w0.z; acc[3] += cv[rr] * w0.w;
;       acc[4] += cv[rr] * w1.x; acc[5] += cv[rr] * w1.y; acc[6] += cv[rr] * w1.z; acc[7] += cv[rr] * w1.w;
;     }
	v_mov_b32_e32 v9, v47
	v_pk_mul_f32 v[8:9], v[8:9], v[22:23]
	v_mov_b32_e32 v39, v46
	v_add_f32_e32 v8, v12, v8
	v_add_f32_e32 v46, v8, v9
	v_mov_b32_e32 v8, v40
	v_mov_b32_e32 v9, v48
	v_pk_mul_f32 v[8:9], v[8:9], v[22:23]
	v_mov_b32_e32 v48, v41
	v_add_f32_e32 v8, v14, v8
	v_add_f32_e32 v14, v8, v9
	v_pk_mul_f32 v[8:9], v[48:49], v[22:23]
	v_pk_mul_f32 v[12:13], v[38:39], v[22:23]
	v_add_f32_e32 v8, v15, v8
	v_add_f32_e32 v15, v8, v9
	v_mov_b32_e32 v8, v34
	v_mov_b32_e32 v9, v42
	v_pk_mul_f32 v[8:9], v[8:9], v[22:23]
	v_mov_b32_e32 v42, v35
	v_add_f32_e32 v8, v50, v8
	v_add_f32_e32 v47, v8, v9
	v_pk_mul_f32 v[8:9], v[42:43], v[22:23]
	v_add_f32_e32 v12, v27, v12
	v_add_f32_e32 v8, v51, v8
	v_add_f32_e32 v48, v8, v9
	v_mov_b32_e32 v8, v36
	v_mov_b32_e32 v9, v44
	v_pk_mul_f32 v[8:9], v[8:9], v[22:23]
	v_mov_b32_e32 v44, v37
	v_add_f32_e32 v8, v10, v8
	v_add_f32_e32 v49, v8, v9
	v_pk_mul_f32 v[8:9], v[44:45], v[22:23]
	v_add_co_u32_e32 v22, vcc, s10, v18
	v_add_f32_e32 v8, v11, v8
	v_add_f32_e32 v50, v8, v9
	v_lshl_add_u64 v[8:9], v[18:19], 0, s[0:1]
	v_addc_co_u32_e32 v23, vcc, 0, v19, vcc
	s_mov_b64 s[0:1], 0x1200
	v_add_f32_e32 v27, v12, v13
	global_load_dwordx4 v[10:13], v[22:23], off
	global_load_dwordx4 v[34:37], v[8:9], off offset:16
	v_lshl_add_u64 v[8:9], v[18:19], 0, s[0:1]
	global_load_dwordx4 v[38:41], v[22:23], off offset:512
	global_load_dwordx4 v[42:45], v[8:9], off offset:16
	s_mov_b64 s[0:1], 0x1400
	s_waitcnt vmcnt(3)
	v_mov_b32_e32 v8, v11
	s_waitcnt vmcnt(1)
	v_mov_b32_e32 v9, v39
	v_pk_mul_f32 v[8:9], v[8:9], v[28:29]
	v_mov_b32_e32 v11, v38
	v_add_f32_e32 v8, v46, v8
	v_add_f32_e32 v46, v8, v9
	v_mov_b32_e32 v8, v12
	v_mov_b32_e32 v9, v40
	v_pk_mul_f32 v[8:9], v[8:9], v[28:29]
	v_mov_b32_e32 v40, v13
	v_add_f32_e32 v8, v14, v8
	v_add_f32_e32 v51, v8, v9
	v_pk_mul_f32 v[8:9], v[40:41], v[28:29]
	v_pk_mul_f32 v[10:11], v[10:11], v[28:29]
	v_add_f32_e32 v8, v15, v8
	v_add_f32_e32 v52, v8, v9
	v_mov_b32_e32 v8, v34
	s_waitcnt vmcnt(0)
	v_mov_b32_e32 v9, v42
	v_pk_mul_f32 v[8:9], v[8:9], v[28:29]
	v_mov_b32_e32 v42, v35
	v_add_f32_e32 v8, v47, v8
	v_add_f32_e32 v47, v8, v9
	v_pk_mul_f32 v[8:9], v[42:43], v[28:29]
	v_add_f32_e32 v10, v27, v10
	v_add_f32_e32 v8, v48, v8
	v_add_f32_e32 v42, v8, v9
	v_mov_b32_e32 v8, v36
	v_mov_b32_e32 v9, v44
	v_pk_mul_f32 v[8:9], v[8:9], v[28:29]
	v_mov_b32_e32 v44, v37
	v_add_f32_e32 v8, v49, v8
	v_add_f32_e32 v43, v8, v9
	v_pk_mul_f32 v[8:9], v[44:45], v[28:29]
	v_lshl_add_u64 v[12:13], v[18:19], 0, s[0:1]
	v_add_f32_e32 v8, v50, v8
	s_mov_b64 s[0:1], 0x1600
	v_add_f32_e32 v27, v10, v11
	v_add_f32_e32 v44, v8, v9
	global_load_dwordx4 v[8:11], v[22:23], off offset:1024
	s_nop 0
	global_load_dwordx4 v[12:15], v[12:13], off offset:16
	v_lshl_add_u64 v[28:29], v[18:19], 0, s[0:1]
	global_load_dwordx4 v[34:37], v[22:23], off offset:1536
	global_load_dwordx4 v[38:41], v[28:29], off offset:16
	s_mov_b64 s[0:1], 0x1800
	s_waitcnt vmcnt(3)
	v_mov_b32_e32 v28, v9
	s_waitcnt vmcnt(1)
	v_mov_b32_e32 v9, v34
	v_pk_mul_f32 v[8:9], v[8:9], v[20:21]
	v_mov_b32_e32 v29, v35
	v_add_f32_e32 v8, v27, v8
	v_add_f32_e32 v27, v8, v9
	v_mov_b32_e32 v8, v10
	v_mov_b32_e32 v9, v36
	v_pk_mul_f32 v[28:29], v[28:29], v[20:21]
	v_pk_mul_f32 v[8:9], v[8:9], v[20:21]
	v_add_f32_e32 v28, v46, v28
	v_add_f32_e32 v8, v51, v8
	v_mov_b32_e32 v36, v11
	v_add_f32_e32 v28, v28, v29
	v_add_f32_e32 v29, v8, v9
	v_pk_mul_f32 v[8:9], v[36:37], v[20:21]
	s_nop 0
	v_add_f32_e32 v8, v52, v8
	v_add_f32_e32 v34, v8, v9
	v_mov_b32_e32 v8, v12
	s_waitcnt vmcnt(0)
	v_mov_b32_e32 v9, v38
	v_pk_mul_f32 v[8:9], v[8:9], v[20:21]
	v_mov_b32_e32 v38, v13
	v_add_f32_e32 v8, v47, v8
	v_add_f32_e32 v35, v8, v9
	v_pk_mul_f32 v[8:9], v[38:39], v[20:21]
	v_lshl_add_u64 v[12:13], v[18:19], 0, s[0:1]
	v_add_f32_e32 v8, v42, v8
	v_add_f32_e32 v46, v8, v9
	v_mov_b32_e32 v8, v14
	v_mov_b32_e32 v9, v40
	v_pk_mul_f32 v[8:9], v[8:9], v[20:21]
	v_mov_b32_e32 v40, v15
	v_add_f32_e32 v8, v43, v8
	v_add_f32_e32 v47, v8, v9
	v_pk_mul_f32 v[8:9], v[40:41], v[20:21]
	s_mov_b64 s[0:1], 0x1a00
	v_add_f32_e32 v8, v44, v8
	v_add_f32_e32 v48, v8, v9
	global_load_dwordx4 v[8:11], v[22:23], off offset:2048
	s_nop 0
	global_load_dwordx4 v[12:15], v[12:13], off offset:16
	v_lshl_add_u64 v[20:21], v[18:19], 0, s[0:1]
	global_load_dwordx4 v[38:41], v[22:23], off offset:2560
	global_load_dwordx4 v[42:45], v[20:21], off offset:16
	s_mov_b64 s[0:1], 0x1c00
	s_waitcnt vmcnt(3)
	v_mov_b32_e32 v20, v9
	s_waitcnt vmcnt(1)
	v_mov_b32_e32 v9, v38
	v_pk_mul_f32 v[8:9], v[8:9], v[16:17]
	v_mov_b32_e32 v21, v39
	v_add_f32_e32 v8, v27, v8
	v_add_f32_e32 v36, v8, v9
	v_mov_b32_e32 v8, v10
	v_mov_b32_e32 v9, v40
	v_pk_mul_f32 v[8:9], v[8:9], v[16:17]
	v_mov_b32_e32 v40, v11
	v_add_f32_e32 v8, v29, v8
	v_add_f32_e32 v37, v8, v9
	v_pk_mul_f32 v[8:9], v[40:41], v[16:17]
	v_pk_mul_f32 v[20:21], v[20:21], v[16:17]
	v_add_f32_e32 v8, v34, v8
	v_add_f32_e32 v34, v8, v9
	v_mov_b32_e32 v8, v12
	s_waitcnt vmcnt(0)
	v_mov_b32_e32 v9, v42
	v_pk_mul_f32 v[8:9], v[8:9], v[16:17]
	v_mov_b32_e32 v42, v13
	v_add_f32_e32 v8, v35, v8
	v_add_f32_e32 v35, v8, v9
	v_pk_mul_f32 v[8:9], v[42:43], v[16:17]
	v_add_f32_e32 v20, v28, v20
	v_add_f32_e32 v8, v46, v8
	v_add_f32_e32 v27, v8, v9
	v_mov_b32_e32 v8, v14
	v_mov_b32_e32 v9, v44
	v_pk_mul_f32 v[8:9], v[8:9], v[16:17]
	v_mov_b32_e32 v44, v15
	v_add_f32_e32 v8, v47, v8
	v_add_f32_e32 v28, v8, v9
	v_pk_mul_f32 v[8:9], v[44:45], v[16:17]
	v_add_f32_e32 v38, v20, v21
	v_add_f32_e32 v8, v48, v8
	v_add_f32_e32 v29, v8, v9
	v_lshl_add_u64 v[8:9], v[18:19], 0, s[0:1]
	s_mov_b64 s[0:1], 0x1e00
	v_lshl_add_u64 v[20:21], v[18:19], 0, s[0:1]
	global_load_dwordx4 v[12:15], v[22:23], off offset:3072
	s_nop 0
	global_load_dwordx4 v[8:11], v[8:9], off offset:16
	s_nop 0
	global_load_dwordx4 v[16:19], v[22:23], off offset:3584
	s_nop 0
	global_load_dwordx4 v[20:23], v[20:21], off offset:16
	s_movk_i32 s0, 0x84
	s_waitcnt vmcnt(3)
; __device__ __forceinline__ float logsig(float x) { return fminf(x, 0.f) - __logf(1.f + __expf(-fabsf(x))); }
; __device__ void gla_prep_unit(const P& p, int layer, int unit, char* smem) {
;     ...
; #pragma unroll
;     for (int rr = 0; rr < 16; ++rr) {
;       const float4 w0 = *(const float4*)(wg + rr * 128), w1 = *(const float4*)(wg + rr * 128 + 4);
;       acc[0] += cv[rr] * w0.x; acc[1] += cv[rr] * w0.y; acc[2] += cv[rr] * w0.z; acc[3] += cv[rr] * w0.w;
;       acc[4] += cv[rr] * w1.x; acc[5] += cv[rr] * w1.y; acc[6] += cv[rr] * w1.z; acc[7] += cv[rr] * w1.w;
;     }
; #pragma unroll
;     for (int i = 0; i < 8; ++i) la[t * 33 + d0 + i] = logsig(acc[i]) * (1.f / 16.f);
	v_mov_b32_e32 v40, v13
	s_waitcnt vmcnt(1)
	v_mov_b32_e32 v13, v16
	v_pk_mul_f32 v[12:13], v[12:13], v[24:25]
	v_mov_b32_e32 v41, v17
	v_add_f32_e32 v12, v36, v12
	v_add_f32_e32 v16, v12, v13
	v_mov_b32_e32 v12, v14
	v_mov_b32_e32 v13, v18
	v_pk_mul_f32 v[12:13], v[12:13], v[24:25]
	v_mov_b32_e32 v18, v15
	v_add_f32_e32 v12, v37, v12
	v_add_f32_e32 v36, v12, v13
	v_pk_mul_f32 v[12:13], v[18:19], v[24:25]
	v_pk_mul_f32 v[40:41], v[40:41], v[24:25]
	v_add_f32_e32 v12, v34, v12
	v_add_f32_e32 v18, v12, v13
	v_mov_b32_e32 v12, v8
	s_waitcnt vmcnt(0)
	v_mov_b32_e32 v13, v20
	v_pk_mul_f32 v[12:13], v[12:13], v[24:25]
	v_mov_b32_e32 v20, v9
	v_add_f32_e32 v8, v35, v12
	v_add_f32_e32 v13, v8, v13
	v_pk_mul_f32 v[8:9], v[20:21], v[24:25]
	v_add_f32_e32 v17, v38, v40
	v_add_f32_e32 v8, v27, v8
	v_add_f32_e32 v19, v8, v9
	v_mov_b32_e32 v8, v10
	v_mov_b32_e32 v9, v22
	v_pk_mul_f32 v[8:9], v[8:9], v[24:25]
	v_mov_b32_e32 v22, v11
	v_add_f32_e32 v8, v28, v8
	v_add_f32_e32 v20, v8, v9
	v_pk_mul_f32 v[8:9], v[22:23], v[24:25]
	v_add_f32_e32 v17, v17, v41
	v_add_f32_e32 v8, v29, v8
	v_add_f32_e32 v8, v8, v9
	v_mul_lo_u32 v9, v31, s0
	v_add3_u32 v12, s45, v9, v26
	v_mul_f32_e64 v9, |v16|, s43
	v_exp_f32_e32 v9, v9
	v_min_f32_e32 v10, 0, v16
	v_and_b32_e32 v16, 64, v198
	v_add_f32_e32 v9, 1.0, v9
	v_cmp_gt_f32_e32 vcc, s92, v9
	s_nop 1
	v_cndmask_b32_e64 v11, 0, 32, vcc
	v_ldexp_f32 v9, v9, v11
	v_log_f32_e32 v9, v9
	s_nop 0
	v_mul_f32_e32 v11, 0x3f317217, v9
	v_fma_f32 v11, v9, s93, -v11
	v_fmac_f32_e32 v11, 0x3377d1cf, v9
	v_fmac_f32_e32 v11, 0x3f317217, v9
	v_cmp_lt_f32_e64 s[0:1], |v9|, s49
	s_nop 1
	v_cndmask_b32_e64 v9, v9, v11, s[0:1]
	v_cndmask_b32_e32 v11, 0, v197, vcc
	v_sub_f32_e32 v14, v9, v11
	v_mul_f32_e64 v9, |v17|, s43
	v_exp_f32_e32 v9, v9
	v_min_f32_e32 v11, 0, v17
	v_and_b32_e32 v17, 63, v30
	v_cmp_gt_u32_e64 s[6:7], 8, v17
	v_add_f32_e32 v9, 1.0, v9
	v_cmp_gt_f32_e32 vcc, s92, v9
	v_cmp_gt_u32_e64 s[8:9], 16, v17
	v_cmp_gt_u32_e64 s[12:13], 32, v17
	v_cndmask_b32_e64 v15, 0, 32, vcc
	v_ldexp_f32 v9, v9, v15
	v_log_f32_e32 v9, v9
	s_nop 0
	v_mul_f32_e32 v15, 0x3f317217, v9
	v_fma_f32 v15, v9, s93, -v15
	v_fmac_f32_e32 v15, 0x3377d1cf, v9
	v_fmac_f32_e32 v15, 0x3f317217, v9
	v_cmp_lt_f32_e64 s[0:1], |v9|, s49
	s_nop 1
	v_cndmask_b32_e64 v9, v9, v15, s[0:1]
	v_cndmask_b32_e32 v15, 0, v197, vcc
	v_sub_f32_e32 v15, v9, v15
	v_mul_f32_e64 v9, |v36|, s43
	v_exp_f32_e32 v9, v9
	v_pk_add_f32 v[10:11], v[10:11], v[14:15] neg_lo:[0,1] neg_hi:[0,1]
	v_add_f32_e32 v9, 1.0, v9
	v_pk_mul_f32 v[10:11], v[10:11], s[2:3] op_sel_hi:[1,0]
	v_cmp_gt_f32_e32 vcc, s92, v9
	ds_write2_b32 v12, v10, v11 offset1:1
	v_min_f32_e32 v10, 0, v36
	v_cndmask_b32_e64 v11, 0, 32, vcc
	v_ldexp_f32 v9, v9, v11
	v_log_f32_e32 v9, v9
	s_nop 0
	v_mul_f32_e32 v11, 0x3f317217, v9
	v_fma_f32 v11, v9, s93, -v11
	v_fmac_f32_e32 v11, 0x3377d1cf, v9
	v_fmac_f32_e32 v11, 0x3f317217, v9
	v_cmp_lt_f32_e64 s[0:1], |v9|, s49
	s_nop 1
	v_cndmask_b32_e64 v9, v9, v11, s[0:1]
	v_cndmask_b32_e32 v11, 0, v197, vcc
	v_sub_f32_e32 v14, v9, v11
	v_mul_f32_e64 v9, |v18|, s43
	v_exp_f32_e32 v9, v9
	v_min_f32_e32 v11, 0, v18
	v_subrev_u32_e32 v18, 32, v198
	v_add_f32_e32 v9, 1.0, v9
	v_cmp_gt_f32_e32 vcc, s92, v9
	s_nop 1
	v_cndmask_b32_e64 v15, 0, 32, vcc
	v_ldexp_f32 v9, v9, v15
	v_log_f32_e32 v9, v9
	s_nop 0
	v_mul_f32_e32 v15, 0x3f317217, v9
	v_fma_f32 v15, v9, s93, -v15
	v_fmac_f32_e32 v15, 0x3377d1cf, v9
	v_fmac_f32_e32 v15, 0x3f317217, v9
	v_cmp_lt_f32_e64 s[0:1], |v9|, s49
	s_nop 1
	v_cndmask_b32_e64 v9, v9, v15, s[0:1]
	v_cndmask_b32_e32 v15, 0, v197, vcc
	v_sub_f32_e32 v15, v9, v15
	v_mul_f32_e64 v9, |v13|, s43
	v_exp_f32_e32 v9, v9
	v_pk_add_f32 v[10:11], v[10:11], v[14:15] neg_lo:[0,1] neg_hi:[0,1]
	v_add_f32_e32 v9, 1.0, v9
	v_pk_mul_f32 v[10:11], v[10:11], s[2:3] op_sel_hi:[1,0]
	v_cmp_gt_f32_e32 vcc, s92, v9
	ds_write2_b32 v12, v10, v11 offset0:2 offset1:3
	v_min_f32_e32 v10, 0, v13
	v_cndmask_b32_e64 v11, 0, 32, vcc
	v_ldexp_f32 v9, v9, v11
	v_log_f32_e32 v9, v9
	s_nop 0
	v_mul_f32_e32 v11, 0x3f317217, v9
	v_fma_f32 v11, v9, s93, -v11
	v_fmac_f32_e32 v11, 0x3377d1cf, v9
	v_fmac_f32_e32 v11, 0x3f317217, v9
	v_cmp_lt_f32_e64 s[0:1], |v9|, s49
	s_nop 1
	v_cndmask_b32_e64 v9, v9, v11, s[0:1]
	v_cndmask_b32_e32 v11, 0, v197, vcc
	v_sub_f32_e32 v14, v9, v11
	v_mul_f32_e64 v9, |v19|, s43
	v_exp_f32_e32 v9, v9
	v_min_f32_e32 v11, 0, v19
	v_add_f32_e32 v9, 1.0, v9
	v_cmp_gt_f32_e32 vcc, s92, v9
	s_nop 1
	v_cndmask_b32_e64 v13, 0, 32, vcc
	v_ldexp_f32 v9, v9, v13
	v_log_f32_e32 v9, v9
	s_nop 0
	v_mul_f32_e32 v13, 0x3f317217, v9
	v_fma_f32 v13, v9, s93, -v13
	v_fmac_f32_e32 v13, 0x3377d1cf, v9
	v_fmac_f32_e32 v13, 0x3f317217, v9
	v_cmp_lt_f32_e64 s[0:1], |v9|, s49
	s_nop 1
	v_cndmask_b32_e64 v9, v9, v13, s[0:1]
	v_cndmask_b32_e32 v13, 0, v197, vcc
	v_sub_f32_e32 v15, v9, v13
	v_mul_f32_e64 v9, |v20|, s43
	v_exp_f32_e32 v9, v9
	v_pk_add_f32 v[10:11], v[10:11], v[14:15] neg_lo:[0,1] neg_hi:[0,1]
	v_add_u32_e32 v13, -4, v198
	v_pk_mul_f32 v[10:11], v[10:11], s[2:3] op_sel_hi:[1,0]
	v_add_f32_e32 v9, 1.0, v9
	v_cmp_gt_f32_e32 vcc, s92, v9
	ds_write2_b32 v12, v10, v11 offset0:4 offset1:5
	v_min_f32_e32 v10, 0, v20
	v_cndmask_b32_e64 v11, 0, 32, vcc
	v_ldexp_f32 v9, v9, v11
	v_log_f32_e32 v9, v9
	s_nop 0
	v_mul_f32_e32 v11, 0x3f317217, v9
	v_fma_f32 v11, v9, s93, -v11
	v_fmac_f32_e32 v11, 0x3377d1cf, v9
	v_fmac_f32_e32 v11, 0x3f317217, v9
	v_cmp_lt_f32_e64 s[0:1], |v9|, s49
	s_nop 1
	v_cndmask_b32_e64 v9, v9, v11, s[0:1]
	v_cndmask_b32_e32 v11, 0, v197, vcc
	v_sub_f32_e32 v14, v9, v11
	v_min_f32_e32 v11, 0, v8
	v_mul_f32_e64 v8, |v8|, s43
	v_exp_f32_e32 v8, v8
	s_nop 0
	v_add_f32_e32 v8, 1.0, v8
; __device__ void gla_prep_unit(const P& p, int layer, int unit, char* smem) {
;     ...
; #pragma unroll
;   for (int i = 0; i < 4; ++i) {
;     const int d = 4 * w + i;
;     const float v0 = la[(2 * lane) * 33 + d], v1 = la[(2 * lane + 1) * 33 + d];
;     const float s = v0 + v1;
;     const float incl = scan_add(s, lane);
;     la[(2 * lane) * 33 + d] = incl - s + v0;
;     la[(2 * lane + 1) * 33 + d] = incl;
;     if (lane == 63) cl[d] = incl;
;   }
	v_cmp_gt_f32_e32 vcc, s92, v8
	s_nop 1
	v_cndmask_b32_e64 v9, 0, 32, vcc
	v_ldexp_f32 v8, v8, v9
	v_log_f32_e32 v8, v8
	s_nop 0
	v_mul_f32_e32 v9, 0x3f317217, v8
	v_fma_f32 v9, v8, s93, -v9
	v_fmac_f32_e32 v9, 0x3377d1cf, v8
	v_fmac_f32_e32 v9, 0x3f317217, v8
	v_cmp_lt_f32_e64 s[0:1], |v8|, s49
	s_nop 1
	v_cndmask_b32_e64 v8, v8, v9, s[0:1]
	v_cndmask_b32_e32 v9, 0, v197, vcc
	v_sub_f32_e32 v15, v8, v9
	v_pk_add_f32 v[8:9], v[10:11], v[14:15] neg_lo:[0,1] neg_hi:[0,1]
	v_add_u32_e32 v14, -8, v198
	v_pk_mul_f32 v[8:9], v[8:9], s[2:3] op_sel_hi:[1,0]
	v_cmp_lt_i32_e64 s[4:5], v14, v16
	v_add_u32_e32 v15, -16, v198
	ds_write2_b32 v12, v8, v9 offset0:6 offset1:7
	v_ashrrev_i32_e32 v8, 4, v30
	s_movk_i32 s0, 0x108
	v_add_u32_e32 v10, -1, v198
	v_add_u32_e32 v11, -2, v198
	v_cndmask_b32_e64 v14, v14, v198, s[4:5]
	v_cmp_lt_i32_e64 s[4:5], v15, v16
	v_and_b32_e32 v20, -4, v8
	v_mad_u32_u24 v9, v17, s0, v196
	v_cmp_lt_i32_e32 vcc, v10, v16
	v_cmp_lt_i32_e64 s[0:1], v11, v16
	v_cmp_lt_i32_e64 s[2:3], v13, v16
	v_cndmask_b32_e64 v15, v15, v198, s[4:5]
	v_cmp_lt_i32_e64 s[4:5], v18, v16
	v_cndmask_b32_e32 v10, v10, v198, vcc
	v_cmp_eq_u32_e32 vcc, 0, v17
	v_cndmask_b32_e64 v11, v11, v198, s[0:1]
	v_cmp_gt_u32_e64 s[0:1], 2, v17
	v_cndmask_b32_e64 v13, v13, v198, s[2:3]
	v_cmp_gt_u32_e64 s[2:3], 4, v17
	v_cndmask_b32_e64 v16, v18, v198, s[4:5]
	v_cmp_eq_u32_e64 s[4:5], 63, v17
	v_lshl_add_u32 v17, v20, 2, v9
	s_waitcnt lgkmcnt(0)
	s_barrier
	ds_read2_b32 v[18:19], v17 offset1:33
	v_lshlrev_b32_e32 v10, 2, v10
	v_lshlrev_b32_e32 v11, 2, v11
	v_lshlrev_b32_e32 v13, 2, v13
	v_lshlrev_b32_e32 v14, 2, v14
	s_waitcnt lgkmcnt(0)
	v_add_f32_e32 v21, v18, v19
	ds_bpermute_b32 v19, v10, v21
	v_lshlrev_b32_e32 v15, 2, v15
	v_lshlrev_b32_e32 v16, 2, v16
	s_waitcnt lgkmcnt(0)
	v_add_f32_e32 v19, v21, v19
	v_cndmask_b32_e32 v19, v19, v21, vcc
	ds_bpermute_b32 v22, v11, v19
	s_waitcnt lgkmcnt(0)
	v_add_f32_e32 v22, v19, v22
	v_cndmask_b32_e64 v19, v22, v19, s[0:1]
	ds_bpermute_b32 v22, v13, v19
	s_waitcnt lgkmcnt(0)
	v_add_f32_e32 v22, v19, v22
	v_cndmask_b32_e64 v19, v22, v19, s[2:3]
	ds_bpermute_b32 v22, v14, v19
	s_waitcnt lgkmcnt(0)
	v_add_f32_e32 v22, v19, v22
	v_cndmask_b32_e64 v19, v22, v19, s[6:7]
	ds_bpermute_b32 v22, v15, v19
	s_waitcnt lgkmcnt(0)
	v_add_f32_e32 v22, v19, v22
	v_cndmask_b32_e64 v22, v22, v19, s[8:9]
	ds_bpermute_b32 v19, v16, v22
	s_waitcnt lgkmcnt(0)
	v_add_f32_e32 v19, v22, v19
	v_cndmask_b32_e64 v22, v19, v22, s[12:13]
	v_sub_f32_e32 v21, v22, v21
	v_add_f32_e32 v18, v18, v21
	ds_write2_b32 v17, v18, v22 offset1:33
	v_lshl_add_u32 v18, v20, 2, v196
	s_and_saveexec_b64 s[16:17], s[4:5]
	ds_write_b32 v18, v19 offset:16896
	s_or_b64 exec, exec, s[16:17]
	ds_read2_b32 v[20:21], v17 offset0:1 offset1:34
	s_waitcnt lgkmcnt(0)
	v_add_f32_e32 v21, v20, v21
	ds_bpermute_b32 v19, v10, v21
	s_waitcnt lgkmcnt(0)
	v_add_f32_e32 v19, v21, v19
	v_cndmask_b32_e32 v19, v19, v21, vcc
	ds_bpermute_b32 v22, v11, v19
	s_waitcnt lgkmcnt(0)
	v_add_f32_e32 v22, v19, v22
	v_cndmask_b32_e64 v19, v22, v19, s[0:1]
	ds_bpermute_b32 v22, v13, v19
	s_waitcnt lgkmcnt(0)
	v_add_f32_e32 v22, v19, v22
	v_cndmask_b32_e64 v19, v22, v19, s[2:3]
	ds_bpermute_b32 v22, v14, v19
	s_waitcnt lgkmcnt(0)
	v_add_f32_e32 v22, v19, v22
	v_cndmask_b32_e64 v19, v22, v19, s[6:7]
	ds_bpermute_b32 v22, v15, v19
	s_waitcnt lgkmcnt(0)
	v_add_f32_e32 v22, v19, v22
	v_cndmask_b32_e64 v22, v22, v19, s[8:9]
	ds_bpermute_b32 v19, v16, v22
	s_waitcnt lgkmcnt(0)
	v_add_f32_e32 v19, v22, v19
	v_cndmask_b32_e64 v22, v19, v22, s[12:13]
	v_sub_f32_e32 v21, v22, v21
	v_add_f32_e32 v20, v20, v21
	ds_write2_b32 v17, v20, v22 offset0:1 offset1:34
	s_and_saveexec_b64 s[16:17], s[4:5]
	ds_write_b32 v18, v19 offset:16900
	s_or_b64 exec, exec, s[16:17]
	ds_read2_b32 v[20:21], v17 offset0:2 offset1:35
	s_waitcnt lgkmcnt(0)
	v_add_f32_e32 v21, v20, v21
	ds_bpermute_b32 v19, v10, v21
	s_waitcnt lgkmcnt(0)
	v_add_f32_e32 v19, v21, v19
	v_cndmask_b32_e32 v19, v19, v21, vcc
	ds_bpermute_b32 v22, v11, v19
	s_waitcnt lgkmcnt(0)
	v_add_f32_e32 v22, v19, v22
	v_cndmask_b32_e64 v19, v22, v19, s[0:1]
	ds_bpermute_b32 v22, v13, v19
	s_waitcnt lgkmcnt(0)
	v_add_f32_e32 v22, v19, v22
	v_cndmask_b32_e64 v19, v22, v19, s[2:3]
	ds_bpermute_b32 v22, v14, v19
	s_waitcnt lgkmcnt(0)
	v_add_f32_e32 v22, v19, v22
	v_cndmask_b32_e64 v19, v22, v19, s[6:7]
	ds_bpermute_b32 v22, v15, v19
	s_waitcnt lgkmcnt(0)
	v_add_f32_e32 v22, v19, v22
	v_cndmask_b32_e64 v22, v22, v19, s[8:9]
	ds_bpermute_b32 v19, v16, v22
	s_waitcnt lgkmcnt(0)
	v_add_f32_e32 v19, v22, v19
	v_cndmask_b32_e64 v22, v19, v22, s[12:13]
	v_sub_f32_e32 v21, v22, v21
	v_add_f32_e32 v20, v20, v21
	ds_write2_b32 v17, v20, v22 offset0:2 offset1:35
	s_and_saveexec_b64 s[16:17], s[4:5]
	ds_write_b32 v18, v19 offset:16904
	s_or_b64 exec, exec, s[16:17]
	v_or_b32_e32 v8, 3, v8
	v_lshl_add_u32 v17, v8, 2, v9
	ds_read2_b32 v[18:19], v17 offset1:33
	s_waitcnt lgkmcnt(0)
	v_add_f32_e32 v19, v18, v19
	ds_bpermute_b32 v9, v10, v19
	s_waitcnt lgkmcnt(0)
	v_add_f32_e32 v9, v19, v9
	v_cndmask_b32_e32 v9, v9, v19, vcc
	ds_bpermute_b32 v10, v11, v9
	s_waitcnt lgkmcnt(0)
	v_add_f32_e32 v10, v9, v10
	v_cndmask_b32_e64 v9, v10, v9, s[0:1]
	ds_bpermute_b32 v10, v13, v9
	s_waitcnt lgkmcnt(0)
	v_add_f32_e32 v10, v9, v10
	v_cndmask_b32_e64 v9, v10, v9, s[2:3]
	ds_bpermute_b32 v10, v14, v9
	s_lshl_b32 s2, s22, 5
	s_waitcnt lgkmcnt(0)
	v_add_f32_e32 v10, v9, v10
	v_cndmask_b32_e64 v9, v10, v9, s[6:7]
	ds_bpermute_b32 v10, v15, v9
	s_waitcnt lgkmcnt(0)
	v_add_f32_e32 v10, v9, v10
	v_cndmask_b32_e64 v10, v10, v9, s[8:9]
	ds_bpermute_b32 v9, v16, v10
	s_waitcnt lgkmcnt(0)
	v_add_f32_e32 v9, v10, v9
	v_cndmask_b32_e64 v10, v9, v10, s[12:13]
	v_sub_f32_e32 v11, v10, v19
	v_add_f32_e32 v11, v18, v11
	ds_write2_b32 v17, v11, v10 offset1:33
	s_and_saveexec_b64 s[0:1], s[4:5]
	v_lshl_add_u32 v8, v8, 2, v196
	ds_write_b32 v8, v9 offset:16896
	s_or_b64 exec, exec, s[0:1]
	v_mad_i64_i32 v[8:9], s[0:1], v33, s54, 0
	s_mov_b32 s0, 0x6180000
	s_waitcnt lgkmcnt(0)
	s_barrier
;   __device__ __forceinline__ bf16* h() const { unsigned o_ = (unsigned)(OFF_h); asm volatile("" : "+s"(o_)); return (bf16*)(ws + o_); }
;   __device__ __forceinline__ bf16* U() const { unsigned o_ = (unsigned)(OFF_U); asm volatile("" : "+s"(o_)); return (bf16*)(ws + o_); }
; #define UNPK8(v, f) { f[0] = lo16(v.x); f[1] = hi16(v.x); f[2] = lo16(v.y); f[3] = hi16(v.y); f[4] = lo16(v.z); f[5] = hi16(v.z); f[6] = lo16(v.w); f[7] = hi16(v.w); }
; __device__ void gla_prep_unit(const P& p, int layer, int unit, char* smem) {
;     ...
;   {
;     const int t = tid >> 2, d0 = (tid & 3) * 8;
;     bf16* qp = p.U() + TROW(t) * US + C_GQ + h * 32 + d0;
;     bf16* kp = p.U() + TROW(t) * US + C_GK + h * 32 + d0;
;     const uint4 qv = qv_pre, kv = kv_pre;
;     float qf[8], kf[8], qd[8], kd[8], kx8[8];
;     UNPK8(qv, qf); UNPK8(kv, kf);
; #pragma unroll
;     for (int i = 0; i < 8; ++i) {
;       const float cum = la[t * 33 + d0 + i];
;       qd[i] = qf[i] * 0.17677669529663687f * __expf(cum);
;       kd[i] = kf[i] * __expf(-cum);
;       kx8[i] = kf[i] * __expf(cl[d0 + i] - cum);
;     }
	s_add_u32 s0, s76, s0
	s_addc_u32 s1, s77, 0
	v_lshl_add_u64 v[10:11], s[0:1], 0, v[8:9]
	s_mov_b32 s0, 0x6180000
	ds_read2_b32 v[14:15], v12 offset1:1
	v_lshlrev_b32_e32 v25, 16, v2
	v_and_b32_e32 v26, 0xffff0000, v2
	v_lshlrev_b32_e32 v18, 16, v0
	v_lshlrev_b32_e32 v23, 16, v1
	s_waitcnt lgkmcnt(0)
	v_mul_f32_e32 v2, 0x3fb8aa3b, v14
	v_exp_f32_e32 v2, v2
	v_and_b32_e32 v24, 0xffff0000, v1
	v_mul_f32_e32 v1, 0x3e3504f3, v18
	v_lshlrev_b32_e32 v33, 16, v5
	v_and_b32_e32 v34, 0xffff0000, v5
	v_mul_f32_e32 v5, v1, v2
	v_mul_f32_e32 v1, 0xbfb8aa3b, v14
	v_exp_f32_e32 v1, v1
	v_and_b32_e32 v22, 0xffff0000, v0
	v_lshlrev_b32_e32 v28, 16, v4
	v_lshl_add_u32 v0, v32, 2, v196
	v_lshlrev_b32_e32 v27, 16, v3
	v_and_b32_e32 v16, 0xffff0000, v3
	v_and_b32_e32 v29, 0xffff0000, v4
	v_mul_f32_e32 v4, v1, v28
	ds_read_b128 v[18:21], v0 offset:16896
	ds_read_b128 v[0:3], v0 offset:16912
	v_lshlrev_b32_e32 v35, 16, v6
	v_and_b32_e32 v36, 0xffff0000, v6
	v_lshlrev_b32_e32 v17, 16, v7
	s_waitcnt lgkmcnt(1)
	v_sub_f32_e32 v6, v18, v14
	v_mul_f32_e32 v6, 0x3fb8aa3b, v6
	v_and_b32_e32 v13, 0xffff0000, v7
	v_exp_f32_e32 v6, v6
	v_mul_f32_e32 v7, 0x3fb8aa3b, v15
	v_exp_f32_e32 v7, v7
	v_mul_f32_e32 v25, 0x3e3504f3, v25
	v_mul_f32_e32 v14, v6, v28
	v_mul_f32_e32 v6, 0x3e3504f3, v22
	v_mul_f32_e32 v7, v6, v7
	v_mul_f32_e32 v6, 0xbfb8aa3b, v15
	v_sub_f32_e32 v15, v19, v15
	ds_read2_b32 v[18:19], v12 offset0:2 offset1:3
	v_mul_f32_e32 v22, 0x3e3504f3, v23
	v_mul_f32_e32 v15, 0x3fb8aa3b, v15
	v_exp_f32_e32 v6, v6
	v_exp_f32_e32 v15, v15
	s_waitcnt lgkmcnt(0)
	v_mul_f32_e32 v23, 0x3fb8aa3b, v18
	v_exp_f32_e32 v23, v23
	v_mul_f32_e32 v6, v6, v29
	v_mul_f32_e32 v15, v15, v29
	s_lshl_b32 s96, s2, 1
	v_mul_f32_e32 v22, v22, v23
	v_mul_f32_e32 v23, 0xbfb8aa3b, v18
	v_sub_f32_e32 v18, v20, v18
	v_mul_f32_e32 v18, 0x3fb8aa3b, v18
	v_exp_f32_e32 v18, v18
	v_exp_f32_e32 v23, v23
	s_add_u32 s0, s76, s0
	s_addc_u32 s1, s77, 0
	v_mul_f32_e32 v20, v18, v33
	v_mul_f32_e32 v18, 0x3e3504f3, v24
	v_mul_f32_e32 v24, 0x3fb8aa3b, v19
	v_exp_f32_e32 v24, v24
	v_mul_f32_e32 v23, v23, v33
	v_lshl_add_u64 v[10:11], v[10:11], 0, s[96:97]
	v_lshl_add_u64 v[8:9], s[0:1], 0, v[8:9]
	v_mul_f32_e32 v24, v18, v24
	v_mul_f32_e32 v18, 0xbfb8aa3b, v19
	v_exp_f32_e32 v18, v18
	v_lshl_add_u64 v[8:9], v[8:9], 0, s[96:97]
	v_lshl_add_u64 v[10:11], v[10:11], 0, v[138:139]
	s_mov_b32 s0, 0x6180000
	v_mul_f32_e32 v28, v18, v34
	v_sub_f32_e32 v18, v21, v19
	v_mul_f32_e32 v18, 0x3fb8aa3b, v18
	v_exp_f32_e32 v18, v18
	v_lshl_add_u64 v[8:9], v[8:9], 0, v[138:139]
	v_cvt_pk_bf16_f32 v4, v4, v6
	s_mov_b32 s2, 0x1aac3000
	v_mul_f32_e32 v21, v18, v34
	ds_read2_b32 v[18:19], v12 offset0:4 offset1:5
	s_waitcnt lgkmcnt(0)
	v_sub_f32_e32 v0, v0, v18
	v_mul_f32_e32 v29, 0x3fb8aa3b, v18
	v_mul_f32_e32 v0, 0x3fb8aa3b, v0
	v_exp_f32_e32 v29, v29
	v_exp_f32_e32 v0, v0
	v_mul_f32_e32 v25, v25, v29
	v_mul_f32_e32 v29, 0xbfb8aa3b, v18
	v_mul_f32_e32 v18, v0, v35
	v_mul_f32_e32 v0, 0x3e3504f3, v26
	v_mul_f32_e32 v26, 0x3fb8aa3b, v19
	v_exp_f32_e32 v26, v26
	v_exp_f32_e32 v29, v29
	v_mul_f32_e32 v26, v0, v26
	v_mul_f32_e32 v0, 0xbfb8aa3b, v19
	v_exp_f32_e32 v0, v0
	v_mul_f32_e32 v29, v29, v35
	v_mul_f32_e32 v33, v0, v36
	v_sub_f32_e32 v0, v1, v19
	v_mul_f32_e32 v0, 0x3fb8aa3b, v0
	v_exp_f32_e32 v0, v0
	v_cvt_pk_bf16_f32 v6, v29, v33
	s_nop 0
	v_mul_f32_e32 v19, v0, v36
	ds_read2_b32 v[0:1], v12 offset0:6 offset1:7
	v_mul_f32_e32 v12, 0x3e3504f3, v27
	s_waitcnt lgkmcnt(0)
; __device__ __forceinline__ bf16 f2bf(float f) { return (bf16)(pk2(f, 0.f) & 0xffffu); }
; template <int DK, int NE>
; __device__ __forceinline__ void local_mfma(const bf16* KxT, const bf16* VxT, float* outc, float* outn) {
;   const int tid = otid(), lane = tid & 63, w = tid >> 6, r = lane & 15, q = lane >> 4;
;   constexpr int NT_ = (DK / 16) * NE;
; #pragma unroll
;   for (int ti = 0; ti < (NT_ + 7) / 8; ++ti) {
;     const int tl = w + 8 * ti;
;     if (tl < NT_) {
;       const int dt = tl / NE, et = tl % NE;
;       f32x4 acc = f32x4{0.f, 0.f, 0.f, 0.f};
; #pragma unroll
;       for (int k0 = 0; k0 < 128; k0 += 32) {
;         const bf16x8 a = *(const bf16x8*)(KxT + (16 * dt + r) * 136 + k0 + q * 8);
;         const bf16x8 bv = *(const bf16x8*)(VxT + (16 * et + r) * 136 + k0 + q * 8);
;         acc = MFMA(a, bv, acc);
;       }
;       if (et < 4) {
; #pragma unroll
;         for (int j = 0; j < 4; ++j) outc[(16 * dt + 4 * q + j) * 64 + 16 * et + r] = acc[j];
;       } else if (r == 0) {
; #pragma unroll
;         for (int j = 0; j < 4; ++j) outn[16 * dt + 4 * q + j] = acc[j];
;       }
;     }
;   }
; }
; __device__ __forceinline__ void load_vxT(const bf16* vsrc, bf16* VxT, int c, int rbase, int rpad) {
;   const int tid = otid(), e0 = (tid >> 7) * 16, t = tid & 127;
;   const bf16* vs = vsrc + TROW(t) * US + e0;
;   const uint4 v0 = *(const uint4*)vs, v1 = *(const uint4*)(vs + 8);
;   VxT[(e0 + 0) * 136 + t] = (bf16)(v0.x & 0xffffu); VxT[(e0 + 1) * 136 + t] = (bf16)(v0.x >> 16);
;   VxT[(e0 + 2) * 136 + t] = (bf16)(v0.y & 0xffffu); VxT[(e0 + 3) * 136 + t] = (bf16)(v0.y >> 16);
;   VxT[(e0 + 4) * 136 + t] = (bf16)(v0.z & 0xffffu); VxT[(e0 + 5) * 136 + t] = (bf16)(v0.z >> 16);
; __device__ void gla_prep_unit(const P& p, int layer, int unit, char* smem) {
;     ...
; #pragma unroll
;     for (int i = 0; i < 8; ++i) KxT[(d0 + i) * 136 + t] = f2bf(kx8[i]);
;     uint4 qo, ko;
;     qo.x = pk2(qd[0], qd[1]); qo.y = pk2(qd[2], qd[3]); qo.z = pk2(qd[4], qd[5]); qo.w = pk2(qd[6], qd[7]);
;     ko.x = pk2(kd[0], kd[1]); ko.y = pk2(kd[2], kd[3]); ko.z = pk2(kd[4], kd[5]); ko.w = pk2(kd[6], kd[7]);
;     *(uint4*)qp = qo; *(uint4*)kp = ko;
;     load_vxT(p.U() + C_GV + h * 64, VxT, c, rbase, rpad);
;   }
;   __syncthreads();
;   local_mfma<32, 4>(KxT, VxT, p.gla_loc() + (size_t)unit * 2048, nullptr);
;   if (tid < 32) p.gla_dec()[unit * 32 + tid] = __expf(cl[tid]);
	v_mul_f32_e32 v27, 0x3fb8aa3b, v0
	v_exp_f32_e32 v27, v27
	s_nop 0
	v_mul_f32_e32 v12, v12, v27
	v_mul_f32_e32 v27, 0xbfb8aa3b, v0
	v_sub_f32_e32 v0, v2, v0
	v_mul_f32_e32 v2, 0x3e3504f3, v16
	v_mul_f32_e32 v16, 0x3fb8aa3b, v1
	v_exp_f32_e32 v16, v16
	v_mul_f32_e32 v0, 0x3fb8aa3b, v0
	v_exp_f32_e32 v27, v27
	v_exp_f32_e32 v0, v0
	v_mul_f32_e32 v16, v2, v16
	v_mul_f32_e32 v2, 0xbfb8aa3b, v1
	v_sub_f32_e32 v1, v3, v1
	v_mul_f32_e32 v1, 0x3fb8aa3b, v1
	v_exp_f32_e32 v2, v2
	v_exp_f32_e32 v1, v1
	v_mul_f32_e32 v27, v27, v17
	v_mul_f32_e32 v0, v0, v17
	v_mul_f32_e32 v17, v2, v13
	v_mul_f32_e32 v1, v1, v13
	v_lshlrev_b32_e32 v2, 1, v31
	v_mul_u32_u24_e32 v13, 0x110, v32
	v_cvt_pk_bf16_f32 v3, v14, v139
	v_add3_u32 v2, s45, v2, v13
	ds_write_b16 v2, v3 offset:17024
	v_cvt_pk_bf16_f32 v3, v15, v139
	ds_write_b16 v2, v3 offset:17296
	v_cvt_pk_bf16_f32 v3, v20, v139
	ds_write_b16 v2, v3 offset:17568
	v_cvt_pk_bf16_f32 v3, v21, v139
	ds_write_b16 v2, v3 offset:17840
	v_cvt_pk_bf16_f32 v3, v18, v139
	v_cvt_pk_bf16_f32 v0, v0, v139
	ds_write_b16 v2, v3 offset:18112
	v_cvt_pk_bf16_f32 v3, v19, v139
	ds_write_b16 v2, v0 offset:18656
	v_cvt_pk_bf16_f32 v0, v1, v139
	ds_write_b16 v2, v3 offset:18384
	ds_write_b16 v2, v0 offset:18928
	v_cvt_pk_bf16_f32 v0, v5, v7
	v_cvt_pk_bf16_f32 v1, v22, v24
	v_cvt_pk_bf16_f32 v2, v25, v26
	v_cvt_pk_bf16_f32 v3, v12, v16
	v_cvt_pk_bf16_f32 v5, v23, v28
	v_cvt_pk_bf16_f32 v7, v27, v17
	s_add_u32 s22, s76, 0x6180000
	s_addc_u32 s23, s77, 0
	s_add_u32 s22, s22, s21
	s_addc_u32 s23, s23, 0
	v_and_b32_e32 v230, 0x7f, v136
	v_cmp_gt_u32_e32 vcc, s44, v230
	s_and_b64 vcc, s[14:15], vcc
	v_mov_b32_e32 v224, s19
	v_mov_b32_e32 v225, s20
	v_cndmask_b32_e32 v224, v224, v225, vcc
	v_ashrrev_i32_e32 v231, 3, v136
	v_add_u32_e32 v224, v224, v230
	v_and_b32_e32 v228, -16, v231
	v_mov_b32_e32 v222, s22
	v_mov_b32_e32 v223, s23
	v_mad_i64_i32 v[222:223], s[24:25], v224, s54, v[222:223]
	v_ashrrev_i32_e32 v229, 31, v228
	v_lshl_add_u64 v[226:227], v[228:229], 1, v[222:223]
	global_load_dwordx4 v[232:235], v[226:227], off offset:2064
	global_load_dwordx4 v[236:239], v[226:227], off offset:2048
	global_store_dwordx4 v[10:11], v[0:3], off offset:1536
	global_store_dwordx4 v[8:9], v[4:7], off offset:1792
	s_add_u32 s0, s76, s0
	v_mov_b32_e32 v0, v136
	s_addc_u32 s1, s77, 0
	s_add_u32 s0, s0, s21
	v_and_b32_e32 v10, 0x7f, v0
	v_cmp_gt_u32_e32 vcc, s44, v10
	s_addc_u32 s1, s1, 0
	s_and_b64 vcc, s[14:15], vcc
	v_mov_b32_e32 v1, s19
	v_mov_b32_e32 v2, s20
	v_cndmask_b32_e32 v1, v1, v2, vcc
	v_ashrrev_i32_e32 v11, 3, v0
	v_add_u32_e32 v2, v1, v10
	v_and_b32_e32 v8, -16, v11
	v_mov_b64_e32 v[0:1], s[0:1]
	v_mad_i64_i32 v[0:1], s[0:1], v2, s54, v[0:1]
	v_ashrrev_i32_e32 v9, 31, v8
	v_lshl_add_u64 v[4:5], v[8:9], 1, v[0:1]
	s_nop 0
	s_nop 0
	s_nop 0
	v_mul_lo_u32 v8, v8, s11
	v_lshlrev_b32_e32 v9, 1, v10
	v_add3_u32 v8, s45, v8, v9
	s_waitcnt vmcnt(2)
	ds_write_b16 v8, v236 offset:25728
	ds_write_b16_d16_hi v8, v236 offset:26000
	ds_write_b16 v8, v237 offset:26272
	ds_write_b16_d16_hi v8, v237 offset:26544
	ds_write_b16 v8, v238 offset:26816
	ds_write_b16_d16_hi v8, v238 offset:27088
	ds_write_b16 v8, v239 offset:27360
	ds_write_b16_d16_hi v8, v239 offset:27632
	ds_write_b16 v8, v232 offset:27904
	ds_write_b16_d16_hi v8, v232 offset:28176
	ds_write_b16 v8, v233 offset:28448
	ds_write_b16_d16_hi v8, v233 offset:28720
	ds_write_b16 v8, v234 offset:28992
	ds_write_b16_d16_hi v8, v234 offset:29264
	ds_write_b16 v8, v235 offset:29536
	v_or_b32_e32 v0, 15, v11
	v_mul_lo_u32 v0, v0, s11
	v_add3_u32 v0, s45, v0, v9
	ds_write_b16_d16_hi v0, v235 offset:25728
	v_mov_b32_e32 v0, v136
	s_waitcnt lgkmcnt(0)
	s_barrier
	s_nop 0
	v_ashrrev_i32_e32 v1, 6, v0
	v_cmp_gt_i32_e32 vcc, 8, v1
	s_and_saveexec_b64 s[0:1], vcc
	s_cbranch_execz .LBB0_260
	v_lshrrev_b32_e32 v2, 30, v1
	v_add_u32_e32 v2, v1, v2
	v_ashrrev_i32_e32 v12, 2, v2
	v_mul_i32_i24_e32 v2, 4, v12
	v_bfe_u32 v13, v0, 4, 2
	v_sub_u32_e32 v1, v1, v2
	v_and_b32_e32 v0, 15, v0
	v_lshl_or_b32 v14, v1, 4, v0
	v_lshl_or_b32 v0, v12, 4, v0
	v_lshlrev_b32_e32 v2, 4, v13
	v_mul_lo_u32 v0, v0, s11
	v_mul_lo_u32 v1, v14, s11
	v_add3_u32 v16, s45, v0, v2
	v_add3_u32 v15, s45, v1, v2
	ds_read_b128 v[0:3], v16 offset:17024
	ds_read_b128 v[4:7], v15 offset:25728
	s_waitcnt lgkmcnt(0)
	v_mfma_f32_16x16x32_bf16 v[0:3], v[0:3], v[4:7], 0
	ds_read_b128 v[4:7], v16 offset:17088
	ds_read_b128 v[8:11], v15 offset:25792
	s_add_u32 s2, s76, s2
	s_addc_u32 s3, s77, 0
	s_waitcnt lgkmcnt(0)
	v_mfma_f32_16x16x32_bf16 v[0:3], v[4:7], v[8:11], v[0:3]
	ds_read_b128 v[4:7], v16 offset:17152
	ds_read_b128 v[8:11], v15 offset:25856
	s_lshl_b32 s4, s33, 13
	s_add_u32 s2, s2, s4
	s_waitcnt lgkmcnt(0)
	v_mfma_f32_16x16x32_bf16 v[0:3], v[4:7], v[8:11], v[0:3]
	ds_read_b128 v[4:7], v16 offset:17216
	ds_read_b128 v[8:11], v15 offset:25920
	s_addc_u32 s3, s3, 0
	s_waitcnt lgkmcnt(0)
	v_mfma_f32_16x16x32_bf16 v[0:3], v[4:7], v[8:11], v[0:3]
	v_lshlrev_b32_e32 v4, 10, v12
	v_lshl_or_b32 v4, v13, 8, v4
	v_add_u32_e32 v4, v4, v14
	v_ashrrev_i32_e32 v5, 31, v4
	v_lshl_add_u64 v[6:7], v[4:5], 2, s[2:3]
	s_nop 2
	global_store_dword v[6:7], v0, off
	v_add_u32_e32 v6, 64, v4
	v_ashrrev_i32_e32 v7, 31, v6
	v_lshl_add_u64 v[6:7], v[6:7], 2, s[2:3]
	v_add_u32_e32 v0, 0x80, v4
	global_store_dword v[6:7], v1, off
	v_ashrrev_i32_e32 v1, 31, v0
	v_lshl_add_u64 v[0:1], v[0:1], 2, s[2:3]
	global_store_dword v[0:1], v2, off
	v_add_u32_e32 v0, 0xc0, v4
	v_ashrrev_i32_e32 v1, 31, v0
	v_lshl_add_u64 v[0:1], v[0:1], 2, s[2:3]
	global_store_dword v[0:1], v3, off
